# v19: MoBA prologue loads merged into one round trip; NSA2 epilogue second sub-block loads hoisted
# speedup vs baseline: 1.0048x; 1.0048x over previous
.LBB0_625:
	global_load_ushort v0, v[154:155], off offset:2820
	global_load_dwordx2 v[66:67], v[146:147], off
	global_load_dwordx2 v[68:69], v[146:147], off offset:64
	global_load_dwordx2 v[70:71], v[146:147], off offset:16
	global_load_dwordx2 v[72:73], v[146:147], off offset:80
	global_load_dwordx2 v[74:75], v[146:147], off offset:32
	global_load_dwordx2 v[76:77], v[146:147], off offset:96
	global_load_dwordx2 v[78:79], v[146:147], off offset:48
	global_load_dwordx2 v[80:81], v[146:147], off offset:112
	global_load_dwordx2 v[206:207], v[148:149], off offset:64
	global_load_dwordx2 v[208:209], v[148:149], off
	global_load_dwordx2 v[210:211], v[148:149], off offset:16
	global_load_dwordx2 v[212:213], v[148:149], off offset:80
	global_load_dwordx2 v[214:215], v[148:149], off offset:32
	global_load_dwordx2 v[216:217], v[148:149], off offset:96
	global_load_dwordx2 v[218:219], v[148:149], off offset:112
	global_load_dwordx2 v[220:221], v[148:149], off offset:48
	global_load_ushort v224, v[152:153], off offset:2820
	ds_bpermute_b32 v82, v166, v151
	s_waitcnt lgkmcnt(0)
	v_add_f32_e32 v82, v151, v82
	v_max_f32_e32 v82, 0xda24260, v82
	v_div_scale_f32 v83, s[0:1], v82, v82, 1.0
	v_rcp_f32_e32 v84, v83
	v_div_scale_f32 v85, s[2:3], 1.0, v82, 1.0
	v_fma_f32 v86, -v83, v84, 1.0
	v_fmac_f32_e32 v84, v86, v84
	v_mul_f32_e32 v86, v85, v84
	v_fma_f32 v87, -v83, v86, v85
	v_fmac_f32_e32 v86, v87, v84
	v_fma_f32 v83, -v83, v86, v85
	s_waitcnt vmcnt(8)
	v_lshlrev_b32_e32 v0, 16, v0
	v_mul_f32_e32 v0, 0xbfb8aa3b, v0
	v_exp_f32_e32 v0, v0
	s_waitcnt vmcnt(7)
	v_lshlrev_b32_e32 v85, 16, v66
	v_and_b32_e32 v66, 0xffff0000, v66
	v_lshlrev_b32_e32 v87, 16, v67
	v_add_f32_e32 v0, 1.0, v0
	v_div_scale_f32 v100, s[0:1], v0, v0, 1.0
	v_rcp_f32_e32 v101, v100
	v_div_scale_f32 v103, vcc, 1.0, v0, 1.0
	v_and_b32_e32 v67, 0xffff0000, v67
	v_fma_f32 v104, -v100, v101, 1.0
	v_fmac_f32_e32 v101, v104, v101
	v_mul_f32_e32 v104, v103, v101
	v_fma_f32 v105, -v100, v104, v103
	v_fmac_f32_e32 v104, v105, v101
	v_fma_f32 v100, -v100, v104, v103
	v_div_fmas_f32 v100, v100, v101, v104
	s_mov_b64 vcc, s[2:3]
	v_div_fmas_f32 v83, v83, v84, v86
	v_div_fixup_f32 v0, v100, v0, 1.0
	v_div_fixup_f32 v82, v83, v82, 1.0
	s_waitcnt vmcnt(6)
	v_lshlrev_b32_e32 v88, 16, v68
	v_and_b32_e32 v68, 0xffff0000, v68
	v_mul_f32_e32 v0, v82, v0
	v_lshlrev_b32_e32 v89, 16, v69
	v_and_b32_e32 v69, 0xffff0000, v69
	s_waitcnt vmcnt(5)
	v_lshlrev_b32_e32 v90, 16, v70
	v_and_b32_e32 v70, 0xffff0000, v70
	v_lshlrev_b32_e32 v91, 16, v71
	v_and_b32_e32 v71, 0xffff0000, v71
	v_fmac_f32_e32 v85, v50, v0
	v_fmac_f32_e32 v66, v51, v0
	v_fmac_f32_e32 v87, v52, v0
	v_fmac_f32_e32 v67, v53, v0
	v_fmac_f32_e32 v88, v34, v0
	v_fmac_f32_e32 v68, v35, v0
	v_cvt_pk_bf16_f32 v34, v85, v66
	v_cvt_pk_bf16_f32 v35, v87, v67
	s_waitcnt vmcnt(4)
	v_lshlrev_b32_e32 v92, 16, v72
	v_and_b32_e32 v72, 0xffff0000, v72
	v_lshlrev_b32_e32 v93, 16, v73
	v_and_b32_e32 v73, 0xffff0000, v73
	s_waitcnt vmcnt(3)
	v_lshlrev_b32_e32 v94, 16, v74
	v_and_b32_e32 v74, 0xffff0000, v74
	v_lshlrev_b32_e32 v95, 16, v75
	v_and_b32_e32 v75, 0xffff0000, v75
	v_fmac_f32_e32 v89, v36, v0
	v_fmac_f32_e32 v69, v37, v0
	v_fmac_f32_e32 v90, v54, v0
	v_fmac_f32_e32 v70, v55, v0
	v_fmac_f32_e32 v91, v56, v0
	v_fmac_f32_e32 v71, v57, v0
	v_cvt_pk_bf16_f32 v36, v88, v68
	v_cvt_pk_bf16_f32 v37, v89, v69
	global_store_dwordx2 v[146:147], v[34:35], off
	global_store_dwordx2 v[146:147], v[36:37], off offset:64
	v_cvt_pk_bf16_f32 v34, v90, v70
	v_cvt_pk_bf16_f32 v35, v91, v71
	s_waitcnt vmcnt(4)
	v_lshlrev_b32_e32 v96, 16, v76
	v_and_b32_e32 v76, 0xffff0000, v76
	v_lshlrev_b32_e32 v97, 16, v77
	v_and_b32_e32 v77, 0xffff0000, v77
	s_waitcnt vmcnt(3)
	v_lshlrev_b32_e32 v98, 16, v78
	v_and_b32_e32 v78, 0xffff0000, v78
	v_lshlrev_b32_e32 v99, 16, v79
	v_and_b32_e32 v79, 0xffff0000, v79
	v_fmac_f32_e32 v92, v38, v0
	v_fmac_f32_e32 v72, v39, v0
	v_fmac_f32_e32 v93, v40, v0
	v_fmac_f32_e32 v73, v41, v0
	v_fmac_f32_e32 v94, v58, v0
	v_fmac_f32_e32 v74, v59, v0
	v_fmac_f32_e32 v95, v60, v0
	v_fmac_f32_e32 v75, v61, v0
	s_waitcnt vmcnt(2)
	v_and_b32_e32 v38, 0xffff0000, v80
	v_lshlrev_b32_e32 v39, 16, v81
	v_and_b32_e32 v40, 0xffff0000, v81
	v_cvt_pk_bf16_f32 v36, v92, v72
	v_cvt_pk_bf16_f32 v37, v93, v73
	global_store_dwordx2 v[146:147], v[34:35], off offset:16
	global_store_dwordx2 v[146:147], v[36:37], off offset:80
	v_cvt_pk_bf16_f32 v34, v94, v74
	v_cvt_pk_bf16_f32 v35, v95, v75
	v_lshlrev_b32_e32 v102, 16, v80
	v_fmac_f32_e32 v96, v42, v0
	v_fmac_f32_e32 v76, v43, v0
	v_fmac_f32_e32 v97, v44, v0
	v_fmac_f32_e32 v77, v45, v0
	v_fmac_f32_e32 v98, v62, v0
	v_fmac_f32_e32 v78, v63, v0
	v_fmac_f32_e32 v99, v64, v0
	v_fmac_f32_e32 v79, v65, v0
	v_fmac_f32_e32 v38, v47, v0
	v_fmac_f32_e32 v39, v48, v0
	v_fmac_f32_e32 v40, v49, v0
	v_cvt_pk_bf16_f32 v36, v96, v76
	v_cvt_pk_bf16_f32 v37, v97, v77
	global_store_dwordx2 v[146:147], v[34:35], off offset:32
	global_store_dwordx2 v[146:147], v[36:37], off offset:96
	v_cvt_pk_bf16_f32 v34, v98, v78
	v_cvt_pk_bf16_f32 v35, v99, v79
	v_fmac_f32_e32 v102, v46, v0
	v_cvt_pk_bf16_f32 v36, v102, v38
	v_cvt_pk_bf16_f32 v37, v39, v40
	s_waitcnt vmcnt(6)
	v_mov_b64_e32 v[38:39], v[206:207]
	v_mov_b64_e32 v[40:41], v[212:213]
	s_nop 0
	global_store_dwordx2 v[146:147], v[34:35], off offset:48
	global_store_dwordx2 v[146:147], v[36:37], off offset:112
	v_mov_b32_e32 v0, v224
	s_nop 0
	v_mov_b64_e32 v[34:35], v[208:209]
	v_mov_b64_e32 v[36:37], v[210:211]
	v_mov_b64_e32 v[42:43], v[214:215]
	ds_bpermute_b32 v46, v166, v150
	v_mov_b64_e32 v[44:45], v[216:217]
	s_waitcnt lgkmcnt(0)
	v_add_f32_e32 v46, v150, v46
	v_max_f32_e32 v50, 0xda24260, v46
	v_div_scale_f32 v51, s[0:1], v50, v50, 1.0
	v_rcp_f32_e32 v52, v51
	v_div_scale_f32 v53, s[2:3], 1.0, v50, 1.0
	v_fma_f32 v48, -v51, v52, 1.0
	v_fmac_f32_e32 v52, v48, v52
	v_mul_f32_e32 v54, v53, v52
	v_fma_f32 v48, -v51, v54, v53
	v_fmac_f32_e32 v54, v48, v52
	v_mov_b64_e32 v[48:49], v[218:219]
	v_mov_b64_e32 v[46:47], v[220:221]
	v_fma_f32 v51, -v51, v54, v53
	s_waitcnt vmcnt(6)
	v_lshlrev_b32_e32 v0, 16, v0
	v_mul_f32_e32 v0, 0xbfb8aa3b, v0
	v_exp_f32_e32 v0, v0
	s_waitcnt vmcnt(4)
	v_lshlrev_b32_e32 v61, 16, v37
	v_lshlrev_b32_e32 v58, 16, v34
	v_and_b32_e32 v34, 0xffff0000, v34
	v_add_f32_e32 v0, 1.0, v0
	v_div_scale_f32 v62, s[0:1], v0, v0, 1.0
	v_rcp_f32_e32 v63, v62
	v_div_scale_f32 v65, vcc, 1.0, v0, 1.0
	v_lshlrev_b32_e32 v59, 16, v35
	v_fma_f32 v66, -v62, v63, 1.0
	v_fmac_f32_e32 v63, v66, v63
	v_mul_f32_e32 v66, v65, v63
	v_fma_f32 v67, -v62, v66, v65
	v_fmac_f32_e32 v66, v67, v63
	v_fma_f32 v62, -v62, v66, v65
	v_div_fmas_f32 v62, v62, v63, v66
	s_mov_b64 vcc, s[2:3]
	v_div_fmas_f32 v51, v51, v52, v54
	v_div_fixup_f32 v0, v62, v0, 1.0
	v_div_fixup_f32 v50, v51, v50, 1.0
	v_mul_f32_e32 v0, v50, v0
	v_fmac_f32_e32 v61, v8, v0
	s_waitcnt vmcnt(3)
	v_and_b32_e32 v8, 0xffff0000, v43
	v_and_b32_e32 v35, 0xffff0000, v35
	v_fmac_f32_e32 v8, v13, v0
	s_waitcnt vmcnt(0)
	v_lshlrev_b32_e32 v13, 16, v46
	v_lshlrev_b32_e32 v53, 16, v38
	v_and_b32_e32 v38, 0xffff0000, v38
	v_lshlrev_b32_e32 v55, 16, v39
	v_and_b32_e32 v39, 0xffff0000, v39
	v_lshlrev_b32_e32 v60, 16, v36
	v_and_b32_e32 v36, 0xffff0000, v36
	v_and_b32_e32 v37, 0xffff0000, v37
	v_fmac_f32_e32 v58, v2, v0
	v_fmac_f32_e32 v34, v3, v0
	v_fmac_f32_e32 v59, v4, v0
	v_fmac_f32_e32 v35, v5, v0
	v_fmac_f32_e32 v13, v14, v0
	v_and_b32_e32 v14, 0xffff0000, v46
	v_cvt_pk_bf16_f32 v2, v58, v34
	v_cvt_pk_bf16_f32 v3, v59, v35
	v_lshlrev_b32_e32 v56, 16, v40
	v_and_b32_e32 v40, 0xffff0000, v40
	v_lshlrev_b32_e32 v57, 16, v41
	v_and_b32_e32 v41, 0xffff0000, v41
	v_lshlrev_b32_e32 v64, 16, v42
	v_fmac_f32_e32 v53, v18, v0
	v_fmac_f32_e32 v38, v19, v0
	v_fmac_f32_e32 v55, v20, v0
	v_fmac_f32_e32 v39, v21, v0
	v_fmac_f32_e32 v60, v6, v0
	v_fmac_f32_e32 v36, v7, v0
	v_fmac_f32_e32 v37, v9, v0
	v_and_b32_e32 v6, 0xffff0000, v42
	v_lshlrev_b32_e32 v7, 16, v43
	v_fmac_f32_e32 v14, v15, v0
	v_lshlrev_b32_e32 v15, 16, v47
	v_cvt_pk_bf16_f32 v4, v53, v38
	v_cvt_pk_bf16_f32 v5, v55, v39
	global_store_dwordx2 v[148:149], v[2:3], off
	global_store_dwordx2 v[148:149], v[4:5], off offset:64
	v_cvt_pk_bf16_f32 v2, v60, v36
	v_cvt_pk_bf16_f32 v3, v61, v37
	v_fmac_f32_e32 v56, v22, v0
	v_fmac_f32_e32 v40, v23, v0
	v_fmac_f32_e32 v57, v24, v0
	v_fmac_f32_e32 v41, v25, v0
	v_fmac_f32_e32 v64, v10, v0
	v_fmac_f32_e32 v6, v11, v0
	v_fmac_f32_e32 v7, v12, v0
	v_lshlrev_b32_e32 v9, 16, v44
	v_and_b32_e32 v10, 0xffff0000, v44
	v_lshlrev_b32_e32 v11, 16, v45
	v_and_b32_e32 v12, 0xffff0000, v45
	v_fmac_f32_e32 v15, v16, v0
	v_and_b32_e32 v16, 0xffff0000, v47
	v_cvt_pk_bf16_f32 v4, v56, v40
	v_cvt_pk_bf16_f32 v5, v57, v41
	global_store_dwordx2 v[148:149], v[2:3], off offset:16
	global_store_dwordx2 v[148:149], v[4:5], off offset:80
	v_cvt_pk_bf16_f32 v2, v64, v6
	v_cvt_pk_bf16_f32 v3, v7, v8
	v_fmac_f32_e32 v9, v26, v0
	v_fmac_f32_e32 v10, v27, v0
	v_fmac_f32_e32 v11, v28, v0
	v_fmac_f32_e32 v12, v29, v0
	v_fmac_f32_e32 v16, v17, v0
	v_lshlrev_b32_e32 v17, 16, v48
	v_and_b32_e32 v18, 0xffff0000, v48
	v_lshlrev_b32_e32 v19, 16, v49
	v_and_b32_e32 v20, 0xffff0000, v49
	v_cvt_pk_bf16_f32 v4, v9, v10
	v_cvt_pk_bf16_f32 v5, v11, v12
	global_store_dwordx2 v[148:149], v[2:3], off offset:32
	global_store_dwordx2 v[148:149], v[4:5], off offset:96
	v_cvt_pk_bf16_f32 v2, v13, v14
	v_cvt_pk_bf16_f32 v3, v15, v16
	s_mov_b64 s[2:3], 0
	s_and_b64 vcc, exec, s[50:51]
	v_fmac_f32_e32 v17, v30, v0
	v_fmac_f32_e32 v18, v31, v0
	v_fmac_f32_e32 v19, v32, v0
	v_fmac_f32_e32 v20, v33, v0
	v_cvt_pk_bf16_f32 v4, v17, v18
	v_cvt_pk_bf16_f32 v5, v19, v20
	global_store_dwordx2 v[148:149], v[2:3], off offset:48
	global_store_dwordx2 v[148:149], v[4:5], off offset:112
	s_cbranch_vccnz .LBB0_622

.LBB0_650:
	v_lshl_add_u32 v72, v185, 1, v185
	v_lshl_add_u64 v[66:67], v[152:153], 1, s[14:15]
	v_lshlrev_b64 v[68:69], 11, v[146:147]
	v_ashrrev_i32_e32 v73, 31, v72
	v_lshl_add_u64 v[68:69], v[66:67], 0, v[68:69]
	v_lshlrev_b32_e32 v0, 3, v186
	v_lshl_add_u64 v[72:73], v[72:73], 1, s[12:13]
	v_lshl_add_u64 v[146:147], v[68:69], 0, v[0:1]
	v_lshl_add_u64 v[154:155], v[72:73], 0, v[154:155]
	global_load_dwordx2 v[68:69], v[146:147], off offset:64
	global_load_dwordx2 v[70:71], v[146:147], off offset:80
	global_load_dwordx2 v[74:75], v[146:147], off offset:96
	global_load_ushort v84, v[154:155], off offset:2818
	global_load_dwordx2 v[72:73], v[146:147], off
	global_load_dwordx2 v[76:77], v[146:147], off offset:16
	global_load_dwordx2 v[78:79], v[146:147], off offset:32
	v_add_co_u32_e32 v226, vcc, 0x10000, v146
	s_nop 1
	v_addc_co_u32_e32 v227, vcc, 0, v147, vcc
	v_lshl_add_u64 v[228:229], v[154:155], 0, s[20:21]
	global_load_dwordx2 v[206:207], v[226:227], off offset:64
	global_load_dwordx2 v[208:209], v[226:227], off
	global_load_dwordx2 v[210:211], v[226:227], off offset:16
	global_load_dwordx2 v[212:213], v[226:227], off offset:80
	global_load_dwordx2 v[214:215], v[226:227], off offset:32
	global_load_dwordx2 v[216:217], v[226:227], off offset:96
	global_load_dwordx2 v[218:219], v[226:227], off offset:112
	global_load_dwordx2 v[220:221], v[226:227], off offset:48
	global_load_ushort v224, v[228:229], off offset:2818
	v_and_b32_e32 v81, 64, v174
	v_xor_b32_e32 v80, 32, v174
	v_add_u32_e32 v81, 64, v81
	v_cmp_lt_i32_e32 vcc, v80, v81
	v_lshl_add_u64 v[152:153], v[154:155], 0, s[20:21]
	s_waitcnt vmcnt(3)
	v_lshlrev_b32_e32 v84, 16, v84
	v_cndmask_b32_e32 v80, v174, v80, vcc
	v_lshlrev_b32_e32 v166, 2, v80
	ds_bpermute_b32 v82, v166, v157
	global_load_dwordx2 v[80:81], v[146:147], off offset:48
	v_mul_f32_e32 v84, 0xbfb8aa3b, v84
	v_exp_f32_e32 v84, v84
	s_waitcnt vmcnt(3)
	v_lshlrev_b32_e32 v95, 16, v72
	s_waitcnt lgkmcnt(0)
	v_add_f32_e32 v82, v157, v82
	v_max_f32_e32 v85, 0xda24260, v82
	global_load_dwordx2 v[82:83], v[146:147], off offset:112
	v_add_f32_e32 v84, 1.0, v84
	v_div_scale_f32 v101, s[0:1], v84, v84, 1.0
	v_div_scale_f32 v86, s[0:1], v85, v85, 1.0
	v_rcp_f32_e32 v102, v101
	v_rcp_f32_e32 v87, v86
	v_div_scale_f32 v103, vcc, 1.0, v84, 1.0
	v_fma_f32 v104, -v101, v102, 1.0
	v_fma_f32 v89, -v86, v87, 1.0
	v_fmac_f32_e32 v102, v104, v102
	v_div_scale_f32 v88, s[2:3], 1.0, v85, 1.0
	v_fmac_f32_e32 v87, v89, v87
	v_mul_f32_e32 v104, v103, v102
	v_mul_f32_e32 v89, v88, v87
	v_fma_f32 v105, -v101, v104, v103
	v_fma_f32 v90, -v86, v89, v88
	v_fmac_f32_e32 v104, v105, v102
	v_fmac_f32_e32 v89, v90, v87
	v_fma_f32 v101, -v101, v104, v103
	v_fma_f32 v86, -v86, v89, v88
	v_div_fmas_f32 v101, v101, v102, v104
	s_mov_b64 vcc, s[2:3]
	v_div_fmas_f32 v86, v86, v87, v89
	v_div_fixup_f32 v84, v101, v84, 1.0
	v_div_fixup_f32 v85, v86, v85, 1.0
	v_lshlrev_b32_e32 v88, 16, v68
	v_and_b32_e32 v68, 0xffff0000, v68
	v_and_b32_e32 v72, 0xffff0000, v72
	v_lshlrev_b32_e32 v96, 16, v73
	v_and_b32_e32 v73, 0xffff0000, v73
	v_mul_f32_e32 v84, v85, v84
	v_lshlrev_b32_e32 v90, 16, v69
	v_and_b32_e32 v69, 0xffff0000, v69
	v_lshlrev_b32_e32 v91, 16, v70
	v_and_b32_e32 v70, 0xffff0000, v70
	s_waitcnt vmcnt(3)
	v_lshlrev_b32_e32 v97, 16, v76
	v_and_b32_e32 v76, 0xffff0000, v76
	v_lshlrev_b32_e32 v98, 16, v77
	v_and_b32_e32 v77, 0xffff0000, v77
	v_fmac_f32_e32 v95, v50, v84
	v_fmac_f32_e32 v72, v51, v84
	v_fmac_f32_e32 v96, v52, v84
	v_fmac_f32_e32 v73, v53, v84
	v_fmac_f32_e32 v88, v34, v84
	v_fmac_f32_e32 v68, v35, v84
	v_cvt_pk_bf16_f32 v34, v95, v72
	v_cvt_pk_bf16_f32 v35, v96, v73
	v_lshlrev_b32_e32 v92, 16, v71
	v_and_b32_e32 v71, 0xffff0000, v71
	s_waitcnt vmcnt(2)
	v_lshlrev_b32_e32 v99, 16, v78
	v_and_b32_e32 v78, 0xffff0000, v78
	v_lshlrev_b32_e32 v100, 16, v79
	v_and_b32_e32 v79, 0xffff0000, v79
	v_fmac_f32_e32 v90, v36, v84
	v_fmac_f32_e32 v69, v37, v84
	v_fmac_f32_e32 v97, v54, v84
	v_fmac_f32_e32 v76, v55, v84
	v_fmac_f32_e32 v98, v56, v84
	v_fmac_f32_e32 v77, v57, v84
	v_fmac_f32_e32 v91, v38, v84
	v_fmac_f32_e32 v70, v39, v84
	v_cvt_pk_bf16_f32 v36, v88, v68
	v_cvt_pk_bf16_f32 v37, v90, v69
	global_store_dwordx2 v[146:147], v[34:35], off
	global_store_dwordx2 v[146:147], v[36:37], off offset:64
	v_cvt_pk_bf16_f32 v34, v97, v76
	v_cvt_pk_bf16_f32 v35, v98, v77
	v_lshlrev_b32_e32 v93, 16, v74
	v_and_b32_e32 v74, 0xffff0000, v74
	v_lshlrev_b32_e32 v94, 16, v75
	v_and_b32_e32 v75, 0xffff0000, v75
	s_waitcnt vmcnt(3)
	v_lshlrev_b32_e32 v38, 16, v80
	v_and_b32_e32 v39, 0xffff0000, v80
	v_fmac_f32_e32 v92, v40, v84
	v_fmac_f32_e32 v71, v41, v84
	v_fmac_f32_e32 v99, v58, v84
	v_fmac_f32_e32 v78, v59, v84
	v_fmac_f32_e32 v100, v60, v84
	v_fmac_f32_e32 v79, v61, v84
	v_fmac_f32_e32 v38, v62, v84
	v_fmac_f32_e32 v39, v63, v84
	v_cvt_pk_bf16_f32 v36, v91, v70
	v_cvt_pk_bf16_f32 v37, v92, v71
	global_store_dwordx2 v[146:147], v[34:35], off offset:16
	global_store_dwordx2 v[146:147], v[36:37], off offset:80
	v_cvt_pk_bf16_f32 v34, v99, v78
	v_cvt_pk_bf16_f32 v35, v100, v79
	v_fmac_f32_e32 v93, v42, v84
	v_fmac_f32_e32 v74, v43, v84
	v_fmac_f32_e32 v94, v44, v84
	v_fmac_f32_e32 v75, v45, v84
	v_cvt_pk_bf16_f32 v36, v93, v74
	v_cvt_pk_bf16_f32 v37, v94, v75
	global_store_dwordx2 v[146:147], v[34:35], off offset:32
	global_store_dwordx2 v[146:147], v[36:37], off offset:96
	v_cvt_pk_bf16_f32 v34, v38, v39
	v_lshlrev_b64 v[38:39], 11, v[148:149]
	v_lshlrev_b32_e32 v40, 16, v81
	v_and_b32_e32 v41, 0xffff0000, v81
	v_lshl_add_u64 v[38:39], v[66:67], 0, v[38:39]
	v_fmac_f32_e32 v40, v64, v84
	v_fmac_f32_e32 v41, v65, v84
	s_waitcnt vmcnt(6)
	v_lshlrev_b32_e32 v42, 16, v82
	v_and_b32_e32 v43, 0xffff0000, v82
	v_lshlrev_b32_e32 v44, 16, v83
	v_and_b32_e32 v45, 0xffff0000, v83
	v_cvt_pk_bf16_f32 v35, v40, v41
	v_lshl_add_u64 v[148:149], v[38:39], 0, v[0:1]
	v_fmac_f32_e32 v42, v46, v84
	v_fmac_f32_e32 v43, v47, v84
	v_fmac_f32_e32 v44, v48, v84
	v_fmac_f32_e32 v45, v49, v84
	v_cvt_pk_bf16_f32 v36, v42, v43
	v_cvt_pk_bf16_f32 v37, v44, v45
	s_waitcnt vmcnt(6)
	v_mov_b64_e32 v[38:39], v[206:207]
	s_nop 0
	global_store_dwordx2 v[146:147], v[34:35], off offset:48
	global_store_dwordx2 v[146:147], v[36:37], off offset:112
	v_mov_b32_e32 v0, v224
	s_nop 0
	v_mov_b64_e32 v[34:35], v[208:209]
	v_mov_b64_e32 v[36:37], v[210:211]
	v_mov_b64_e32 v[40:41], v[212:213]
	v_mov_b64_e32 v[42:43], v[214:215]
	ds_bpermute_b32 v46, v166, v156
	v_mov_b64_e32 v[44:45], v[216:217]
	s_waitcnt lgkmcnt(0)
	v_add_f32_e32 v46, v156, v46
	v_max_f32_e32 v50, 0xda24260, v46
	v_div_scale_f32 v51, s[0:1], v50, v50, 1.0
	v_rcp_f32_e32 v52, v51
	v_div_scale_f32 v53, s[2:3], 1.0, v50, 1.0
	v_fma_f32 v48, -v51, v52, 1.0
	v_fmac_f32_e32 v52, v48, v52
	v_mul_f32_e32 v54, v53, v52
	v_fma_f32 v48, -v51, v54, v53
	v_fmac_f32_e32 v54, v48, v52
	v_mov_b64_e32 v[48:49], v[218:219]
	v_mov_b64_e32 v[46:47], v[220:221]
	v_fma_f32 v51, -v51, v54, v53
	s_waitcnt vmcnt(7)
	v_lshlrev_b32_e32 v0, 16, v0
	v_mul_f32_e32 v0, 0xbfb8aa3b, v0
	v_exp_f32_e32 v0, v0
	v_lshlrev_b32_e32 v55, 16, v39
	v_and_b32_e32 v39, 0xffff0000, v39
	s_waitcnt vmcnt(5)
	v_lshlrev_b32_e32 v60, 16, v36
	v_add_f32_e32 v0, 1.0, v0
	v_div_scale_f32 v58, s[0:1], v0, v0, 1.0
	v_rcp_f32_e32 v59, v58
	v_div_scale_f32 v61, vcc, 1.0, v0, 1.0
	v_lshlrev_b32_e32 v53, 16, v38
	v_fma_f32 v62, -v58, v59, 1.0
	v_fmac_f32_e32 v59, v62, v59
	v_mul_f32_e32 v62, v61, v59
	v_fma_f32 v63, -v58, v62, v61
	v_fmac_f32_e32 v62, v63, v59
	v_fma_f32 v58, -v58, v62, v61
	v_div_fmas_f32 v58, v58, v59, v62
	s_mov_b64 vcc, s[2:3]
	v_div_fmas_f32 v51, v51, v52, v54
	v_div_fixup_f32 v0, v58, v0, 1.0
	v_div_fixup_f32 v50, v51, v50, 1.0
	v_mul_f32_e32 v0, v50, v0
	v_fmac_f32_e32 v55, v20, v0
	v_fmac_f32_e32 v39, v21, v0
	v_fmac_f32_e32 v60, v6, v0
	v_and_b32_e32 v6, 0xffff0000, v36
	s_waitcnt vmcnt(4)
	v_and_b32_e32 v20, 0xffff0000, v41
	s_waitcnt vmcnt(3)
	v_lshlrev_b32_e32 v21, 16, v42
	v_fmac_f32_e32 v6, v7, v0
	v_lshlrev_b32_e32 v7, 16, v37
	v_fmac_f32_e32 v20, v25, v0
	v_fmac_f32_e32 v21, v10, v0
	v_and_b32_e32 v10, 0xffff0000, v42
	s_waitcnt vmcnt(0)
	v_lshlrev_b32_e32 v25, 16, v46
	v_and_b32_e32 v38, 0xffff0000, v38
	v_lshlrev_b32_e32 v56, 16, v34
	v_and_b32_e32 v34, 0xffff0000, v34
	v_lshlrev_b32_e32 v57, 16, v35
	v_and_b32_e32 v35, 0xffff0000, v35
	v_fmac_f32_e32 v7, v8, v0
	v_and_b32_e32 v8, 0xffff0000, v37
	v_fmac_f32_e32 v10, v11, v0
	v_lshlrev_b32_e32 v11, 16, v43
	v_fmac_f32_e32 v25, v14, v0
	v_and_b32_e32 v14, 0xffff0000, v46
	s_add_i32 s0, s84, -8
	v_fmac_f32_e32 v56, v2, v0
	v_fmac_f32_e32 v34, v3, v0
	v_fmac_f32_e32 v57, v4, v0
	v_fmac_f32_e32 v35, v5, v0
	v_fmac_f32_e32 v53, v18, v0
	v_fmac_f32_e32 v38, v19, v0
	v_fmac_f32_e32 v8, v9, v0
	v_lshlrev_b32_e32 v9, 16, v40
	v_and_b32_e32 v18, 0xffff0000, v40
	v_lshlrev_b32_e32 v19, 16, v41
	v_fmac_f32_e32 v11, v12, v0
	v_and_b32_e32 v12, 0xffff0000, v43
	v_fmac_f32_e32 v14, v15, v0
	v_lshlrev_b32_e32 v15, 16, v47
	v_cvt_pk_bf16_f32 v2, v56, v34
	v_cvt_pk_bf16_f32 v3, v57, v35
	v_cvt_pk_bf16_f32 v4, v53, v38
	v_cvt_pk_bf16_f32 v5, v55, v39
	s_cmp_gt_u32 s61, 1
	v_fmac_f32_e32 v9, v22, v0
	v_fmac_f32_e32 v18, v23, v0
	v_fmac_f32_e32 v19, v24, v0
	v_fmac_f32_e32 v12, v13, v0
	v_lshlrev_b32_e32 v13, 16, v44
	v_and_b32_e32 v22, 0xffff0000, v44
	v_lshlrev_b32_e32 v23, 16, v45
	v_and_b32_e32 v24, 0xffff0000, v45
	v_fmac_f32_e32 v15, v16, v0
	v_and_b32_e32 v16, 0xffff0000, v47
	global_store_dwordx2 v[148:149], v[2:3], off
	global_store_dwordx2 v[148:149], v[4:5], off offset:64
	v_cvt_pk_bf16_f32 v2, v60, v6
	v_cvt_pk_bf16_f32 v3, v7, v8
	v_cvt_pk_bf16_f32 v4, v9, v18
	v_cvt_pk_bf16_f32 v5, v19, v20
	s_cselect_b32 s85, s0, 0
	v_fmac_f32_e32 v13, v26, v0
	v_fmac_f32_e32 v22, v27, v0
	v_fmac_f32_e32 v23, v28, v0
	v_fmac_f32_e32 v24, v29, v0
	v_fmac_f32_e32 v16, v17, v0
	v_lshlrev_b32_e32 v17, 16, v48
	v_and_b32_e32 v26, 0xffff0000, v48
	v_lshlrev_b32_e32 v27, 16, v49
	v_and_b32_e32 v28, 0xffff0000, v49
	global_store_dwordx2 v[148:149], v[2:3], off offset:16
	global_store_dwordx2 v[148:149], v[4:5], off offset:80
	v_cvt_pk_bf16_f32 v2, v21, v10
	v_cvt_pk_bf16_f32 v3, v11, v12
	v_cvt_pk_bf16_f32 v4, v13, v22
	v_cvt_pk_bf16_f32 v5, v23, v24
	s_cmp_gt_u32 s85, s84
	v_fmac_f32_e32 v17, v30, v0
	v_fmac_f32_e32 v26, v31, v0
	v_fmac_f32_e32 v27, v32, v0
	v_fmac_f32_e32 v28, v33, v0
	global_store_dwordx2 v[148:149], v[2:3], off offset:32
	global_store_dwordx2 v[148:149], v[4:5], off offset:96
	v_cvt_pk_bf16_f32 v2, v25, v14
	v_cvt_pk_bf16_f32 v3, v15, v16
	v_cvt_pk_bf16_f32 v4, v17, v26
	v_cvt_pk_bf16_f32 v5, v27, v28
	global_store_dwordx2 v[148:149], v[2:3], off offset:48
	global_store_dwordx2 v[148:149], v[4:5], off offset:112
	s_cbranch_scc1 .LBB0_624
	s_lshl_b32 s84, s85, 6
	v_add_u32_e32 v0, s84, v183
	v_med3_i32 v0, v0, 0, v141
	v_mul_u32_u24_e32 v0, 0x600, v0
	v_lshl_add_u64 v[2:3], v[0:1], 1, s[44:45]
	v_lshlrev_b32_e32 v0, 1, v150
	v_lshl_add_u64 v[2:3], v[2:3], 0, v[0:1]
	global_load_dwordx4 v[18:21], v[2:3], off offset:2048
	global_load_dwordx4 v[22:25], v[2:3], off offset:2176
	s_add_i32 s60, s60, -11
	v_add3_u32 v0, s60, v181, v151
	v_sub_u32_e32 v0, v0, v184
	s_barrier
	v_mov_b32_e32 v16, v1
	v_mov_b32_e32 v17, v1
	v_mov_b32_e32 v2, v1
	v_mov_b32_e32 v3, v1
	v_mov_b32_e32 v4, v1
	v_mov_b32_e32 v5, v1
	v_mov_b32_e32 v6, v1
	v_mov_b32_e32 v7, v1
	v_mov_b32_e32 v8, v1
	v_mov_b32_e32 v9, v1
	v_mov_b32_e32 v10, v1
	v_mov_b32_e32 v11, v1
	v_mov_b32_e32 v12, v1
	v_mov_b32_e32 v13, v1
	v_mov_b32_e32 v14, v1
	v_mov_b32_e32 v15, v1
	v_subrev_u32_e32 v181, s84, v0
	v_mov_b32_e32 v0, v1
	v_mov_b64_e32 v[48:49], v[16:17]
	v_mov_b64_e32 v[64:65], v[16:17]
	s_mov_b32 s86, 0
	v_add_u32_e32 v167, 0xffffff80, v182
	v_add_u32_e32 v168, 0xfffffe01, v182
	v_add_u32_e32 v169, 0xfffffe21, v182
	v_add_u32_e32 v183, 0xfffffe40, v182
	v_add_u32_e32 v185, 0xfffffe20, v182
	v_add_u32_e32 v182, 0xffffffa0, v182
	v_mov_b32_e32 v186, 0xf149f2ca
	v_mov_b64_e32 v[46:47], v[14:15]
	v_mov_b64_e32 v[44:45], v[12:13]
	v_mov_b64_e32 v[42:43], v[10:11]
	v_mov_b64_e32 v[40:41], v[8:9]
	v_mov_b64_e32 v[38:39], v[6:7]
	v_mov_b64_e32 v[36:37], v[4:5]
	v_mov_b64_e32 v[34:35], v[2:3]
	v_mov_b64_e32 v[62:63], v[14:15]
	v_mov_b64_e32 v[60:61], v[12:13]
	v_mov_b64_e32 v[58:59], v[10:11]
	v_mov_b64_e32 v[56:57], v[8:9]
	v_mov_b64_e32 v[54:55], v[6:7]
	v_mov_b64_e32 v[52:53], v[4:5]
	v_mov_b64_e32 v[50:51], v[2:3]
	v_mov_b32_e32 v187, 0xf149f2ca
	v_mov_b64_e32 v[150:151], v[0:1]
	s_waitcnt vmcnt(1)
	ds_write_b128 v140, v[18:21]
	s_waitcnt vmcnt(0)
	ds_write_b128 v142, v[22:25] offset:18432
	s_waitcnt lgkmcnt(0)
	s_barrier
	ds_read_b32 v184, v175 offset:43524
	v_mov_b64_e32 v[32:33], v[16:17]
	v_mov_b64_e32 v[30:31], v[14:15]
	v_mov_b64_e32 v[28:29], v[12:13]
	v_mov_b64_e32 v[26:27], v[10:11]
	v_mov_b64_e32 v[24:25], v[8:9]
	v_mov_b64_e32 v[22:23], v[6:7]
	v_mov_b64_e32 v[20:21], v[4:5]
	v_mov_b64_e32 v[18:19], v[2:3]
	s_branch .LBB0_653

.Lmoba_skipfill:
	v_and_b32_e32 v253, 32, v200
	v_add_u32_e32 v253, 0x1e000, v253
	s_mov_b32 s91, 0x1d094
	s_mov_b32 s32, 0x1d114
	s_xor_b64 s[72:73], s[2:3], -1
	s_and_b64 s[0:1], s[2:3], exec
	s_cselect_b32 s97, s96, s95
	v_ashrrev_i32_e32 v80, 8, v78
	v_lshl_add_u32 v62, s97, 1, v80
	v_and_b32_e32 v81, 0xc0, v78
	v_and_b32_e32 v79, 31, v78
	v_lshl_or_b32 v83, v62, 8, v81
	v_or_b32_e32 v0, v83, v79
	v_ashrrev_i32_e32 v1, 31, v0
	v_lshl_add_u64 v[172:173], s[44:45], 0, v[0:1]
	v_bfe_u32 v82, v78, 5, 1
	v_mad_u64_u32 v[0:1], s[0:1], v172, s84, v[170:171]
	v_mad_i32_i24 v1, v173, s84, v1
	v_lshlrev_b32_e32 v168, 4, v82
	v_lshl_add_u64 v[0:1], v[0:1], 0, v[168:169]
	global_load_dwordx4 v[20:23], v[0:1], off offset:32
	global_load_dwordx4 v[28:31], v[0:1], off
	global_load_dwordx4 v[16:19], v[0:1], off offset:96
	global_load_dwordx4 v[24:27], v[0:1], off offset:64
	v_add_co_u32_e32 v144, vcc, 0x28000, v0
	s_nop 1
	v_addc_co_u32_e32 v145, vcc, 0, v1, vcc
	global_load_dwordx4 v[124:127], v[144:145], off offset:32
	global_load_dwordx4 v[132:135], v[144:145], off
	global_load_dwordx4 v[120:123], v[144:145], off offset:96
	global_load_dwordx4 v[128:131], v[144:145], off offset:64
	v_ashrrev_i32_e32 v146, 3, v200
	v_med3_i32 v146, v146, 0, v201
	v_mul_u32_u24_e32 v146, 0xa00, v146
	v_mov_b32_e32 v147, 0
	v_lshl_add_u64 v[146:147], v[146:147], 1, s[68:69]
	v_lshlrev_b32_e32 v144, 4, v200
	v_and_b32_e32 v144, 0x70, v144
	v_mov_b32_e32 v145, 0
	v_lshl_add_u64 v[146:147], v[146:147], 0, v[144:145]
	global_load_dwordx4 v[136:139], v[146:147], off
	global_load_dwordx4 v[140:143], v[146:147], off offset:1536
	v_and_b32_e32 v0, 32, v78
	v_mov_b32_e32 v1, v169
	v_lshl_add_u64 v[12:13], s[34:35], 0, v[0:1]
	v_mov_b32_e32 v63, 0
	v_lshl_add_u64 v[0:1], v[12:13], 0, s[50:51]
	v_cmp_lt_i32_e32 vcc, 0, v62
	v_mov_b32_e32 v64, 0
	s_waitcnt vmcnt(3)
	v_lshlrev_b32_e32 v15, 16, v20
	s_waitcnt vmcnt(2)
	v_lshlrev_b32_e32 v14, 16, v28
	v_and_b32_e32 v45, 0xffff0000, v20
	v_and_b32_e32 v44, 0xffff0000, v28
	v_lshlrev_b32_e32 v43, 16, v21
	v_lshlrev_b32_e32 v42, 16, v29
	v_and_b32_e32 v41, 0xffff0000, v21
	v_and_b32_e32 v40, 0xffff0000, v29
	v_lshlrev_b32_e32 v39, 16, v22
	v_lshlrev_b32_e32 v38, 16, v30
	v_and_b32_e32 v37, 0xffff0000, v22
	v_and_b32_e32 v36, 0xffff0000, v30
	v_lshlrev_b32_e32 v35, 16, v23
	v_lshlrev_b32_e32 v34, 16, v31
	v_and_b32_e32 v33, 0xffff0000, v23
	v_and_b32_e32 v32, 0xffff0000, v31
	s_waitcnt vmcnt(1)
	v_lshlrev_b32_e32 v49, 16, v16
	s_waitcnt vmcnt(0)
	v_lshlrev_b32_e32 v48, 16, v24
	v_and_b32_e32 v61, 0xffff0000, v16
	v_and_b32_e32 v60, 0xffff0000, v24
	v_lshlrev_b32_e32 v59, 16, v17
	v_lshlrev_b32_e32 v58, 16, v25
	v_and_b32_e32 v57, 0xffff0000, v17
	v_and_b32_e32 v56, 0xffff0000, v25
	v_lshlrev_b32_e32 v55, 16, v18
	v_lshlrev_b32_e32 v54, 16, v26
	v_and_b32_e32 v53, 0xffff0000, v18
	v_and_b32_e32 v52, 0xffff0000, v26
	v_lshlrev_b32_e32 v51, 16, v19
	v_lshlrev_b32_e32 v50, 16, v27
	v_and_b32_e32 v47, 0xffff0000, v19
	v_and_b32_e32 v46, 0xffff0000, v27
	s_and_saveexec_b64 s[2:3], vcc
	s_cbranch_execz .LBB0_1293
	ds_read_b128 v[2:5], v253 offset:0
	ds_read_b128 v[6:9], v253 offset:64
	ds_read_b128 v[64:67], v253 offset:16
	ds_read_b128 v[68:71], v253 offset:80
	ds_read_b128 v[72:75], v253 offset:128
	ds_read_b128 v[84:87], v253 offset:192
	ds_read_b128 v[88:91], v253 offset:144
	ds_read_b128 v[92:95], v253 offset:208
	s_waitcnt lgkmcnt(7)
	v_mov_b32_e32 v10, v2
	s_waitcnt lgkmcnt(6)
	v_mov_b32_e32 v11, v6
	v_mov_b32_e32 v6, v3
	v_pk_mul_f32 v[6:7], v[6:7], v[44:45]
	v_mov_b32_e32 v2, v4
	v_mov_b32_e32 v3, v8
	v_mov_b32_e32 v8, v5
	s_waitcnt lgkmcnt(4)
	v_mov_b32_e32 v5, v68
	v_mov_b32_e32 v68, v65
	v_mov_b32_e32 v65, v70
	v_mov_b32_e32 v70, v67
	s_waitcnt lgkmcnt(2)
	v_mov_b32_e32 v67, v84
	v_mov_b32_e32 v84, v73
	v_pk_fma_f32 v[6:7], v[10:11], v[14:15], v[6:7]
	v_mov_b32_e32 v4, v64
	v_mov_b32_e32 v64, v66
	v_mov_b32_e32 v66, v72
	v_pk_mul_f32 v[84:85], v[84:85], v[60:61]
	v_pk_fma_f32 v[2:3], v[2:3], v[42:43], v[6:7]
	v_mov_b32_e32 v72, v74
	v_mov_b32_e32 v73, v86
	v_pk_fma_f32 v[10:11], v[66:67], v[48:49], v[84:85]
	v_pk_fma_f32 v[2:3], v[8:9], v[40:41], v[2:3]
	v_mov_b32_e32 v86, v75
	v_pk_fma_f32 v[6:7], v[72:73], v[58:59], v[10:11]
	v_pk_fma_f32 v[2:3], v[4:5], v[38:39], v[2:3]
	s_waitcnt lgkmcnt(1)
	v_mov_b32_e32 v74, v88
	s_waitcnt lgkmcnt(0)
	v_mov_b32_e32 v75, v92
	v_pk_fma_f32 v[6:7], v[86:87], v[56:57], v[6:7]
	v_pk_fma_f32 v[2:3], v[68:69], v[36:37], v[2:3]
	v_mov_b32_e32 v92, v89
	v_pk_fma_f32 v[4:5], v[74:75], v[54:55], v[6:7]
	v_pk_fma_f32 v[2:3], v[64:65], v[34:35], v[2:3]
	v_mov_b32_e32 v76, v90
	v_mov_b32_e32 v77, v94
	v_pk_fma_f32 v[4:5], v[92:93], v[52:53], v[4:5]
	v_pk_fma_f32 v[2:3], v[70:71], v[32:33], v[2:3]
	v_mov_b32_e32 v94, v91
	v_pk_fma_f32 v[4:5], v[76:77], v[50:51], v[4:5]
	v_add_f32_e32 v2, 0, v2
	v_add_f32_e32 v6, v2, v3
	v_pk_fma_f32 v[2:3], v[94:95], v[46:47], v[4:5]
	s_nop 0
	v_add_f32_e32 v2, v6, v2
	v_add_f32_e32 v64, v2, v3

.LBB0_1306:
	v_and_b32_e32 v38, 1, v37
	v_cmp_eq_u32_e64 s[18:19], 0, v38
	s_or_b64 s[18:19], s[18:19], s[14:15]
	v_and_b32_e32 v40, 2, v37
	v_cndmask_b32_e64 v39, v35, v199, s[18:19]
	v_cndmask_b32_e64 v38, 0, -1, s[18:19]
	v_cmp_ne_u32_e64 s[18:19], 0, v40
	v_cmp_gt_f32_e64 s[20:21], v34, v39
	s_and_b64 s[18:19], s[18:19], s[20:21]
	v_cndmask_b32_e64 v39, v39, v34, s[18:19]
	v_and_b32_e32 v40, 4, v37
	v_cndmask_b32_e64 v38, v38, 1, s[18:19]
	v_cmp_ne_u32_e64 s[18:19], 0, v40
	v_cmp_gt_f32_e64 s[20:21], v33, v39
	s_and_b64 s[18:19], s[18:19], s[20:21]
	v_cndmask_b32_e64 v39, v39, v33, s[18:19]
	v_and_b32_e32 v40, 8, v37
	v_cndmask_b32_e64 v38, v38, 2, s[18:19]
	v_cmp_ne_u32_e64 s[18:19], 0, v40
	v_cmp_gt_f32_e64 s[20:21], v32, v39
	s_and_b64 s[18:19], s[18:19], s[20:21]
	v_cndmask_b32_e64 v39, v39, v32, s[18:19]
	v_and_b32_e32 v40, 16, v37
	v_cndmask_b32_e64 v38, v38, 3, s[18:19]
	v_cmp_ne_u32_e64 s[18:19], 0, v40
	v_cmp_gt_f32_e64 s[20:21], v15, v39
	s_and_b64 s[18:19], s[18:19], s[20:21]
	v_cndmask_b32_e64 v39, v39, v15, s[18:19]
	v_and_b32_e32 v40, 32, v37
	v_cndmask_b32_e64 v38, v38, 4, s[18:19]
	v_cmp_ne_u32_e64 s[18:19], 0, v40
	v_cmp_gt_f32_e64 s[20:21], v14, v39
	s_and_b64 s[18:19], s[18:19], s[20:21]
	v_cndmask_b32_e64 v39, v39, v14, s[18:19]
	v_and_b32_e32 v40, 64, v37
	v_cndmask_b32_e64 v38, v38, 5, s[18:19]
	v_cmp_ne_u32_e64 s[18:19], 0, v40
	v_cmp_gt_f32_e64 s[20:21], v36, v39
	s_and_b64 s[18:19], s[18:19], s[20:21]
	v_cndmask_b32_e64 v38, v38, 6, s[18:19]
	v_lshlrev_b32_e64 v39, v38, 1
	v_cmp_lt_i32_e64 s[18:19], -1, v38
	v_not_b32_e32 v40, v39
	s_add_i32 s0, s0, -1
	v_cndmask_b32_e64 v38, 0, v39, s[18:19]
	v_or_b32_e32 v205, v38, v205
	v_cndmask_b32_e64 v38, -1, v40, s[18:19]
	s_cmp_lg_u32 s0, 0
	v_and_b32_e32 v37, v38, v37
	s_cbranch_scc1 .LBB0_1306
	v_or_b32_e32 v176, 32, v172
	v_mov_b64_e32 v[14:15], s[66:67]
	v_mad_u64_u32 v[14:15], s[0:1], v176, s84, v[14:15]
	v_mad_i32_i24 v15, v173, s84, v15
	v_lshlrev_b32_e32 v32, 1, v174
	v_mov_b32_e32 v33, v169
	v_lshl_add_u64 v[14:15], v[14:15], 0, v[32:33]
	v_mov_b64_e32 v[52:53], v[124:125]
	v_mov_b64_e32 v[54:55], v[126:127]
	v_mov_b64_e32 v[60:61], v[132:133]
	v_mov_b64_e32 v[62:63], v[134:135]
	v_mov_b64_e32 v[48:49], v[120:121]
	v_mov_b64_e32 v[50:51], v[122:123]
	v_mov_b64_e32 v[56:57], v[128:129]
	v_mov_b64_e32 v[58:59], v[130:131]
	v_mov_b32_e32 v86, 0
	v_mov_b32_e32 v87, 0
	s_waitcnt vmcnt(3)
	v_lshlrev_b32_e32 v15, 16, v52
	s_waitcnt vmcnt(2)
	v_lshlrev_b32_e32 v14, 16, v60
	v_and_b32_e32 v45, 0xffff0000, v52
	v_and_b32_e32 v44, 0xffff0000, v60
	v_lshlrev_b32_e32 v43, 16, v53
	v_lshlrev_b32_e32 v42, 16, v61
	v_and_b32_e32 v41, 0xffff0000, v53
	v_and_b32_e32 v40, 0xffff0000, v61
	v_lshlrev_b32_e32 v39, 16, v54
	v_lshlrev_b32_e32 v38, 16, v62
	v_and_b32_e32 v37, 0xffff0000, v54
	v_and_b32_e32 v36, 0xffff0000, v62
	v_lshlrev_b32_e32 v35, 16, v55
	v_lshlrev_b32_e32 v34, 16, v63
	v_and_b32_e32 v33, 0xffff0000, v55
	v_and_b32_e32 v32, 0xffff0000, v63
	s_waitcnt vmcnt(1)
	v_lshlrev_b32_e32 v65, 16, v48
	s_waitcnt vmcnt(0)
	v_lshlrev_b32_e32 v64, 16, v56
	v_and_b32_e32 v77, 0xffff0000, v48
	v_and_b32_e32 v76, 0xffff0000, v56
	v_lshlrev_b32_e32 v75, 16, v49
	v_lshlrev_b32_e32 v74, 16, v57
	v_and_b32_e32 v73, 0xffff0000, v49
	v_and_b32_e32 v72, 0xffff0000, v57
	v_lshlrev_b32_e32 v71, 16, v50
	v_lshlrev_b32_e32 v70, 16, v58
	v_and_b32_e32 v69, 0xffff0000, v50
	v_and_b32_e32 v68, 0xffff0000, v58
	v_lshlrev_b32_e32 v67, 16, v51
	v_lshlrev_b32_e32 v66, 16, v59
	v_and_b32_e32 v47, 0xffff0000, v51
	v_and_b32_e32 v46, 0xffff0000, v59
	s_and_saveexec_b64 s[14:15], vcc
	s_cbranch_execz .LBB0_1309
	ds_read_b128 v[88:91], v253 offset:0
	ds_read_b128 v[92:95], v253 offset:64
	ds_read_b128 v[96:99], v253 offset:16
	ds_read_b128 v[100:103], v253 offset:80
	ds_read_b128 v[104:107], v253 offset:128
	ds_read_b128 v[108:111], v253 offset:192
	ds_read_b128 v[112:115], v253 offset:144
	ds_read_b128 v[116:119], v253 offset:208
	s_waitcnt lgkmcnt(7)
	v_mov_b32_e32 v0, v88
	s_waitcnt lgkmcnt(6)
	v_mov_b32_e32 v1, v92
	v_mov_b32_e32 v92, v89
	v_pk_mul_f32 v[92:93], v[92:93], v[44:45]
	v_mov_b32_e32 v88, v90
	v_mov_b32_e32 v89, v94
	v_mov_b32_e32 v94, v91
	s_waitcnt lgkmcnt(4)
	v_mov_b32_e32 v91, v100
	v_mov_b32_e32 v100, v97
	v_mov_b32_e32 v97, v102
	v_mov_b32_e32 v102, v99
	s_waitcnt lgkmcnt(2)
	v_mov_b32_e32 v99, v108
	v_mov_b32_e32 v108, v105
	v_pk_fma_f32 v[0:1], v[0:1], v[14:15], v[92:93]
	v_mov_b32_e32 v90, v96
	v_mov_b32_e32 v96, v98
	v_mov_b32_e32 v98, v104
	v_pk_mul_f32 v[108:109], v[108:109], v[76:77]
	v_pk_fma_f32 v[0:1], v[88:89], v[42:43], v[0:1]
	v_mov_b32_e32 v104, v106
	v_mov_b32_e32 v105, v110
	v_pk_fma_f32 v[92:93], v[98:99], v[64:65], v[108:109]
	v_pk_fma_f32 v[0:1], v[94:95], v[40:41], v[0:1]
	v_mov_b32_e32 v110, v107
	v_pk_fma_f32 v[88:89], v[104:105], v[74:75], v[92:93]
	v_pk_fma_f32 v[0:1], v[90:91], v[38:39], v[0:1]
	s_waitcnt lgkmcnt(1)
	v_mov_b32_e32 v106, v112
	s_waitcnt lgkmcnt(0)
	v_mov_b32_e32 v107, v116
	v_pk_fma_f32 v[88:89], v[110:111], v[72:73], v[88:89]
	v_pk_fma_f32 v[0:1], v[100:101], v[36:37], v[0:1]
	v_mov_b32_e32 v116, v113
	v_pk_fma_f32 v[88:89], v[106:107], v[70:71], v[88:89]
	v_pk_fma_f32 v[0:1], v[96:97], v[34:35], v[0:1]
	v_mov_b32_e32 v112, v114
	v_mov_b32_e32 v113, v118
	v_pk_fma_f32 v[88:89], v[116:117], v[68:69], v[88:89]
	v_pk_fma_f32 v[0:1], v[102:103], v[32:33], v[0:1]
	v_mov_b32_e32 v118, v115
	v_pk_fma_f32 v[88:89], v[112:113], v[66:67], v[88:89]
	v_add_f32_e32 v0, 0, v0
	v_add_f32_e32 v87, v0, v1
	v_pk_fma_f32 v[0:1], v[118:119], v[46:47], v[88:89]
	s_nop 0
	v_add_f32_e32 v0, v87, v0
	v_add_f32_e32 v87, v0, v1

.LBB0_1322:
	v_and_b32_e32 v5, 1, v85
	v_cmp_eq_u32_e64 s[2:3], 0, v5
	s_or_b64 s[2:3], s[2:3], vcc
	v_and_b32_e32 v9, 2, v85
	v_cndmask_b32_e64 v8, v0, v199, s[2:3]
	v_cndmask_b32_e64 v5, 0, -1, s[2:3]
	v_cmp_ne_u32_e64 s[2:3], 0, v9
	v_cmp_gt_f32_e64 s[4:5], v1, v8
	s_and_b64 s[2:3], s[2:3], s[4:5]
	v_cndmask_b32_e64 v8, v8, v1, s[2:3]
	v_and_b32_e32 v9, 4, v85
	v_cndmask_b32_e64 v5, v5, 1, s[2:3]
	v_cmp_ne_u32_e64 s[2:3], 0, v9
	v_cmp_gt_f32_e64 s[4:5], v2, v8
	s_and_b64 s[2:3], s[2:3], s[4:5]
	v_cndmask_b32_e64 v8, v8, v2, s[2:3]
	v_and_b32_e32 v9, 8, v85
	v_cndmask_b32_e64 v5, v5, 2, s[2:3]
	v_cmp_ne_u32_e64 s[2:3], 0, v9
	v_cmp_gt_f32_e64 s[4:5], v3, v8
	s_and_b64 s[2:3], s[2:3], s[4:5]
	v_cndmask_b32_e64 v8, v8, v3, s[2:3]
	v_and_b32_e32 v9, 16, v85
	v_cndmask_b32_e64 v5, v5, 3, s[2:3]
	v_cmp_ne_u32_e64 s[2:3], 0, v9
	v_cmp_gt_f32_e64 s[4:5], v6, v8
	s_and_b64 s[2:3], s[2:3], s[4:5]
	v_cndmask_b32_e64 v8, v8, v6, s[2:3]
	v_and_b32_e32 v9, 32, v85
	v_cndmask_b32_e64 v5, v5, 4, s[2:3]
	v_cmp_ne_u32_e64 s[2:3], 0, v9
	v_cmp_gt_f32_e64 s[4:5], v7, v8
	s_and_b64 s[2:3], s[2:3], s[4:5]
	v_cndmask_b32_e64 v8, v8, v7, s[2:3]
	v_and_b32_e32 v9, 64, v85
	v_cndmask_b32_e64 v5, v5, 5, s[2:3]
	v_cmp_ne_u32_e64 s[2:3], 0, v9
	v_cmp_gt_f32_e64 s[4:5], v4, v8
	s_and_b64 s[2:3], s[2:3], s[4:5]
	v_cndmask_b32_e64 v5, v5, 6, s[2:3]
	v_lshlrev_b32_e64 v8, v5, 1
	v_cmp_lt_i32_e64 s[2:3], -1, v5
	v_not_b32_e32 v9, v8
	s_add_i32 s0, s0, -1
	v_cndmask_b32_e64 v5, 0, v8, s[2:3]
	v_or_b32_e32 v175, v5, v175
	v_cndmask_b32_e64 v5, -1, v9, s[2:3]
	s_cmp_lg_u32 s0, 0
	v_and_b32_e32 v85, v5, v85
	s_cbranch_scc1 .LBB0_1322
	v_ashrrev_i32_e32 v74, 3, v78
	v_med3_i32 v0, v74, 0, v201
	v_mul_u32_u24_e32 v0, 0xa00, v0
	v_mov_b32_e32 v1, v169
	v_lshlrev_b32_e32 v2, 4, v78
	v_lshl_add_u64 v[0:1], v[0:1], 1, s[68:69]
	v_and_b32_e32 v72, 0x70, v2
	v_mov_b32_e32 v73, v169
	v_lshl_add_u64 v[0:1], v[0:1], 0, v[72:73]
	v_mov_b64_e32 v[64:65], v[136:137]
	v_mov_b64_e32 v[66:67], v[138:139]
	v_mov_b64_e32 v[68:69], v[140:141]
	v_mov_b64_e32 v[70:71], v[142:143]
	v_lshlrev_b32_e32 v32, 7, v78
	v_lshlrev_b32_e32 v75, 4, v84
	v_lshrrev_b32_e32 v33, 2, v78
	v_and_b32_e32 v34, 16, v78
	v_lshlrev_b32_e32 v36, 2, v78
	v_and_b32_e32 v77, 0xffffe000, v32
	v_mul_lo_u32 v78, v74, s86
	v_add3_u32 v75, 0, v77, v75
	v_add3_u32 v180, 0, v78, v72
	ds_write_b128 v75, v[28:31] offset:53248
	ds_write_b128 v75, v[60:63] offset:57344
	ds_write_b128 v75, v[20:23] offset:54272
	ds_write_b128 v75, v[52:55] offset:58368
	ds_write_b128 v75, v[24:27] offset:55296
	ds_write_b128 v75, v[56:59] offset:59392
	ds_write_b128 v75, v[16:19] offset:56320
	ds_write_b128 v75, v[48:51] offset:60416
	v_mad_u64_u32 v[184:185], s[0:1], v74, 48, v[180:181]
	s_waitcnt lgkmcnt(0)
	s_barrier
	v_lshlrev_b32_e32 v76, 2, v82
	v_mul_u32_u24_e32 v35, 0x90, v79
	v_lshl_or_b32 v208, v80, 8, v81
	v_mov_b32_e32 v14, v169
	v_mov_b32_e32 v15, v169
	v_and_or_b32 v80, v33, 3, v76
	v_and_or_b32 v81, v36, 12, v34
	s_lshl_b32 s20, s97, 3
	s_lshl_b32 s19, s97, 9
	v_mov_b32_e32 v0, v169
	v_mov_b32_e32 v1, v169
	v_mov_b32_e32 v2, v169
	v_mov_b32_e32 v3, v169
	v_mov_b32_e32 v4, v169
	v_mov_b32_e32 v5, v169
	v_mov_b32_e32 v6, v169
	v_mov_b32_e32 v7, v169
	v_mov_b32_e32 v8, v169
	v_mov_b32_e32 v9, v169
	v_mov_b32_e32 v10, v169
	v_mov_b32_e32 v11, v169
	v_mov_b32_e32 v12, v169
	v_mov_b32_e32 v13, v169
	v_add3_u32 v209, 0, v35, v168
	v_add_u32_e32 v79, v208, v79
	v_mov_b32_e32 v168, v169
	v_mov_b64_e32 v[46:47], v[14:15]
	v_lshl_add_u64 v[182:183], s[68:69], 0, v[72:73]
	v_mul_u32_u24_e32 v72, 0xc0, v80
	v_lshlrev_b32_e32 v73, 1, v81
	v_mov_b64_e32 v[62:63], v[14:15]
	v_mov_b64_e32 v[30:31], v[14:15]
	s_mov_b32 s18, 0
	v_or_b32_e32 v206, 31, v83
	v_or_b32_e32 v207, 63, v83
	v_mov_b32_e32 v213, 0xf149f2ca
	s_add_i32 s20, s20, 8
	v_add_u32_e32 v210, 64, v74
	s_add_i32 s21, s19, 0x200
	v_mov_b64_e32 v[44:45], v[12:13]
	v_mov_b64_e32 v[42:43], v[10:11]
	v_mov_b64_e32 v[40:41], v[8:9]
	v_mov_b64_e32 v[38:39], v[6:7]
	v_mov_b64_e32 v[36:37], v[4:5]
	v_mov_b64_e32 v[34:35], v[2:3]
	v_mov_b64_e32 v[32:33], v[0:1]
	v_sub_u32_e32 v211, v79, v76
	v_add3_u32 v185, 0, v72, v73
	v_mov_b64_e32 v[60:61], v[12:13]
	v_mov_b64_e32 v[58:59], v[10:11]
	v_mov_b64_e32 v[56:57], v[8:9]
	v_mov_b64_e32 v[54:55], v[6:7]
	v_mov_b64_e32 v[52:53], v[4:5]
	v_mov_b64_e32 v[50:51], v[2:3]
	v_mov_b64_e32 v[48:49], v[0:1]
	v_mov_b64_e32 v[28:29], v[12:13]
	v_mov_b64_e32 v[26:27], v[10:11]
	v_mov_b64_e32 v[24:25], v[8:9]
	v_mov_b64_e32 v[22:23], v[6:7]
	v_mov_b64_e32 v[20:21], v[4:5]
	s_waitcnt vmcnt(1)
	ds_write_b128 v180, v[64:67]
	s_waitcnt vmcnt(0)
	ds_write_b128 v184, v[68:71] offset:18432
	s_waitcnt lgkmcnt(0)
	s_barrier
	ds_read_b32 v212, v169 offset:43524
	ds_read_b128 v[128:131], v75 offset:53248
	ds_read_b128 v[132:135], v75 offset:54272
	ds_read_b128 v[136:139], v75 offset:55296
	ds_read_b128 v[140:143], v75 offset:58368
	ds_read_b128 v[144:147], v75 offset:59392
	ds_read_b128 v[148:151], v75 offset:57344
	ds_read_b128 v[152:155], v75 offset:56320
	ds_read_b128 v[156:159], v75 offset:60416
	v_mov_b64_e32 v[18:19], v[2:3]
	v_mov_b64_e32 v[16:17], v[0:1]
	v_mov_b32_e32 v214, 0xf149f2ca
	s_mov_b32 s97, 0
	s_mov_b32 s0, 0
	v_mov_b64_e32 v[178:179], v[168:169]
